# adds adaLN GEMV load pipelining and RG-LRU conv tap load hoist on top of v14 (bit-identical numerics)
# speedup vs baseline: 1.0558x; 1.0146x over previous
; template <int PART>
; __device__ __forceinline__ void prologue(const Params& p, unsigned char* lds) {
;     ...
;     for (int u = blockIdx.x; u < 2 * 96; u += G) {
;         const int l = u / 96, n = (u % 96) * 64 + (tid & 63), kp = tid >> 6;
;         const float* w = p.in[I_ADAW] + (size_t)l * 1024 * 6144 + n;
;         float a0 = 0.f, a1 = 0.f, a2 = 0.f, a3 = 0.f;
;         for (int k = kp * 128; k < kp * 128 + 128; ++k) { const float wv = w[(size_t)k * 6144]; a0 += sc[k] * wv; a1 += sc[1024 + k] * wv; a2 += sc[2048 + k] * wv; a3 += sc[3072 + k] * wv; }
.LBB0_78:
	v_lshl_add_u64 v[16:17], v[6:7], 0, s[2:3]
	v_add_co_u32_e64 v18, s[0:1], s4, v16
	global_load_dword v32, v[16:17], off
	s_nop 0
	v_addc_co_u32_e64 v19, s[0:1], 0, v17, s[0:1]
	v_add_co_u32_e64 v20, s[0:1], s5, v16
	s_add_u32 s2, s2, 0x18000
	s_nop 0
	v_addc_co_u32_e64 v21, s[0:1], 0, v17, s[0:1]
	v_add_co_u32_e64 v16, s[0:1], s6, v16
	s_addc_u32 s3, s3, 0
	s_nop 0
	v_addc_co_u32_e64 v17, s[0:1], 0, v17, s[0:1]
	global_load_dword v34, v[18:19], off
	global_load_dword v36, v[20:21], off
	global_load_dword v38, v[16:17], off
	v_lshl_add_u64 v[16:17], v[6:7], 0, s[2:3]
	v_add_co_u32_e64 v18, s[0:1], s4, v16
	global_load_dword v44, v[16:17], off
	s_nop 0
	v_addc_co_u32_e64 v19, s[0:1], 0, v17, s[0:1]
	v_add_co_u32_e64 v20, s[0:1], s5, v16
	s_add_u32 s2, s2, 0x18000
	s_nop 0
	v_addc_co_u32_e64 v21, s[0:1], 0, v17, s[0:1]
	v_add_co_u32_e64 v16, s[0:1], s6, v16
	s_addc_u32 s3, s3, 0
	s_nop 0
	v_addc_co_u32_e64 v17, s[0:1], 0, v17, s[0:1]
	global_load_dword v46, v[18:19], off
	global_load_dword v48, v[20:21], off
	global_load_dword v50, v[16:17], off
	v_lshl_add_u64 v[16:17], v[6:7], 0, s[2:3]
	v_add_co_u32_e64 v18, s[0:1], s4, v16
	global_load_dword v52, v[16:17], off
	s_nop 0
	v_addc_co_u32_e64 v19, s[0:1], 0, v17, s[0:1]
	v_add_co_u32_e64 v20, s[0:1], s5, v16
	s_add_u32 s2, s2, 0x18000
	s_nop 0
	v_addc_co_u32_e64 v21, s[0:1], 0, v17, s[0:1]
	v_add_co_u32_e64 v16, s[0:1], s6, v16
	s_addc_u32 s3, s3, 0
	s_nop 0
	v_addc_co_u32_e64 v17, s[0:1], 0, v17, s[0:1]
	global_load_dword v54, v[18:19], off
	global_load_dword v56, v[20:21], off
	global_load_dword v58, v[16:17], off
	v_lshl_add_u64 v[16:17], v[6:7], 0, s[2:3]
	v_add_co_u32_e64 v18, s[0:1], s4, v16
	global_load_dword v60, v[16:17], off
	s_nop 0
	v_addc_co_u32_e64 v19, s[0:1], 0, v17, s[0:1]
	v_add_co_u32_e64 v20, s[0:1], s5, v16
	s_add_u32 s2, s2, 0x18000
	s_nop 0
	v_addc_co_u32_e64 v21, s[0:1], 0, v17, s[0:1]
	v_add_co_u32_e64 v16, s[0:1], s6, v16
	s_addc_u32 s3, s3, 0
	s_nop 0
	v_addc_co_u32_e64 v17, s[0:1], 0, v17, s[0:1]
	global_load_dword v62, v[18:19], off
	global_load_dword v64, v[20:21], off
	global_load_dword v66, v[16:17], off
.Lada_loop:
	ds_read_b128 v[16:19], v5
	ds_read_b128 v[20:23], v5 offset:4096
	ds_read_b128 v[24:27], v5 offset:8192
	ds_read_b128 v[28:31], v5 offset:12288
	v_add_u32_e32 v5, 16, v5
	s_waitcnt lgkmcnt(3)
	v_mov_b32_e32 v41, v16
	s_waitcnt lgkmcnt(2)
	v_mov_b32_e32 v40, v20
	s_waitcnt lgkmcnt(1)
	v_mov_b32_e32 v43, v24
	s_waitcnt lgkmcnt(0)
	v_mov_b32_e32 v42, v28
	v_mov_b32_e32 v16, v21
	v_mov_b32_e32 v24, v29
	v_mov_b32_e32 v20, v22
	v_mov_b32_e32 v21, v18
	v_mov_b32_e32 v28, v30
	v_mov_b32_e32 v29, v26
	v_mov_b32_e32 v18, v23
	v_mov_b32_e32 v26, v31
	s_waitcnt vmcnt(12)
	v_pk_fma_f32 v[10:11], v[32:33], v[40:41], v[10:11] op_sel_hi:[0,1,1]
	v_pk_fma_f32 v[8:9], v[32:33], v[42:43], v[8:9] op_sel_hi:[0,1,1]
	v_pk_fma_f32 v[10:11], v[34:35], v[16:17], v[10:11] op_sel_hi:[0,1,1]
	v_pk_fma_f32 v[8:9], v[34:35], v[24:25], v[8:9] op_sel_hi:[0,1,1]
	v_pk_fma_f32 v[10:11], v[36:37], v[20:21], v[10:11] op_sel_hi:[0,1,1]
	v_pk_fma_f32 v[8:9], v[36:37], v[28:29], v[8:9] op_sel_hi:[0,1,1]
	v_pk_fma_f32 v[10:11], v[38:39], v[18:19], v[10:11] op_sel_hi:[0,1,1]
	v_pk_fma_f32 v[8:9], v[38:39], v[26:27], v[8:9] op_sel_hi:[0,1,1]
	v_lshl_add_u64 v[16:17], v[6:7], 0, s[2:3]
	v_add_co_u32_e64 v18, s[0:1], s4, v16
	global_load_dword v32, v[16:17], off
	s_nop 0
	v_addc_co_u32_e64 v19, s[0:1], 0, v17, s[0:1]
	v_add_co_u32_e64 v20, s[0:1], s5, v16
	s_add_u32 s2, s2, 0x18000
	s_nop 0
	v_addc_co_u32_e64 v21, s[0:1], 0, v17, s[0:1]
	v_add_co_u32_e64 v16, s[0:1], s6, v16
	s_addc_u32 s3, s3, 0
	s_nop 0
	v_addc_co_u32_e64 v17, s[0:1], 0, v17, s[0:1]
	global_load_dword v34, v[18:19], off
	global_load_dword v36, v[20:21], off
	global_load_dword v38, v[16:17], off
	ds_read_b128 v[16:19], v5
	ds_read_b128 v[20:23], v5 offset:4096
	ds_read_b128 v[24:27], v5 offset:8192
	ds_read_b128 v[28:31], v5 offset:12288
	v_add_u32_e32 v5, 16, v5
	s_waitcnt lgkmcnt(3)
	v_mov_b32_e32 v41, v16
	s_waitcnt lgkmcnt(2)
	v_mov_b32_e32 v40, v20
	s_waitcnt lgkmcnt(1)
	v_mov_b32_e32 v43, v24
	s_waitcnt lgkmcnt(0)
	v_mov_b32_e32 v42, v28
	v_mov_b32_e32 v16, v21
	v_mov_b32_e32 v24, v29
	v_mov_b32_e32 v20, v22
	v_mov_b32_e32 v21, v18
	v_mov_b32_e32 v28, v30
	v_mov_b32_e32 v29, v26
	v_mov_b32_e32 v18, v23
	v_mov_b32_e32 v26, v31
	s_waitcnt vmcnt(12)
	v_pk_fma_f32 v[10:11], v[44:45], v[40:41], v[10:11] op_sel_hi:[0,1,1]
	v_pk_fma_f32 v[8:9], v[44:45], v[42:43], v[8:9] op_sel_hi:[0,1,1]
	v_pk_fma_f32 v[10:11], v[46:47], v[16:17], v[10:11] op_sel_hi:[0,1,1]
	v_pk_fma_f32 v[8:9], v[46:47], v[24:25], v[8:9] op_sel_hi:[0,1,1]
	v_pk_fma_f32 v[10:11], v[48:49], v[20:21], v[10:11] op_sel_hi:[0,1,1]
	v_pk_fma_f32 v[8:9], v[48:49], v[28:29], v[8:9] op_sel_hi:[0,1,1]
	v_pk_fma_f32 v[10:11], v[50:51], v[18:19], v[10:11] op_sel_hi:[0,1,1]
	v_pk_fma_f32 v[8:9], v[50:51], v[26:27], v[8:9] op_sel_hi:[0,1,1]
	v_lshl_add_u64 v[16:17], v[6:7], 0, s[2:3]
	v_add_co_u32_e64 v18, s[0:1], s4, v16
	global_load_dword v44, v[16:17], off
	s_nop 0
	v_addc_co_u32_e64 v19, s[0:1], 0, v17, s[0:1]
	v_add_co_u32_e64 v20, s[0:1], s5, v16
	s_add_u32 s2, s2, 0x18000
	s_nop 0
	v_addc_co_u32_e64 v21, s[0:1], 0, v17, s[0:1]
	v_add_co_u32_e64 v16, s[0:1], s6, v16
	s_addc_u32 s3, s3, 0
	s_nop 0
	v_addc_co_u32_e64 v17, s[0:1], 0, v17, s[0:1]
	global_load_dword v46, v[18:19], off
	global_load_dword v48, v[20:21], off
	global_load_dword v50, v[16:17], off
	ds_read_b128 v[16:19], v5
	ds_read_b128 v[20:23], v5 offset:4096
	ds_read_b128 v[24:27], v5 offset:8192
	ds_read_b128 v[28:31], v5 offset:12288
	v_add_u32_e32 v5, 16, v5
	s_waitcnt lgkmcnt(3)
; template <int PART>
; __device__ __forceinline__ void prologue(const Params& p, unsigned char* lds) {
;     ...
;         for (int k = kp * 128; k < kp * 128 + 128; ++k) { const float wv = w[(size_t)k * 6144]; a0 += sc[k] * wv; a1 += sc[1024 + k] * wv; a2 += sc[2048 + k] * wv; a3 += sc[3072 + k] * wv; }
	v_mov_b32_e32 v41, v16
	s_waitcnt lgkmcnt(2)
	v_mov_b32_e32 v40, v20
	s_waitcnt lgkmcnt(1)
	v_mov_b32_e32 v43, v24
	s_waitcnt lgkmcnt(0)
	v_mov_b32_e32 v42, v28
	v_mov_b32_e32 v16, v21
	v_mov_b32_e32 v24, v29
	v_mov_b32_e32 v20, v22
	v_mov_b32_e32 v21, v18
	v_mov_b32_e32 v28, v30
	v_mov_b32_e32 v29, v26
	v_mov_b32_e32 v18, v23
	v_mov_b32_e32 v26, v31
	s_waitcnt vmcnt(12)
	v_pk_fma_f32 v[10:11], v[52:53], v[40:41], v[10:11] op_sel_hi:[0,1,1]
	v_pk_fma_f32 v[8:9], v[52:53], v[42:43], v[8:9] op_sel_hi:[0,1,1]
	v_pk_fma_f32 v[10:11], v[54:55], v[16:17], v[10:11] op_sel_hi:[0,1,1]
	v_pk_fma_f32 v[8:9], v[54:55], v[24:25], v[8:9] op_sel_hi:[0,1,1]
	v_pk_fma_f32 v[10:11], v[56:57], v[20:21], v[10:11] op_sel_hi:[0,1,1]
	v_pk_fma_f32 v[8:9], v[56:57], v[28:29], v[8:9] op_sel_hi:[0,1,1]
	v_pk_fma_f32 v[10:11], v[58:59], v[18:19], v[10:11] op_sel_hi:[0,1,1]
	v_pk_fma_f32 v[8:9], v[58:59], v[26:27], v[8:9] op_sel_hi:[0,1,1]
	v_lshl_add_u64 v[16:17], v[6:7], 0, s[2:3]
	v_add_co_u32_e64 v18, s[0:1], s4, v16
	global_load_dword v52, v[16:17], off
	s_nop 0
	v_addc_co_u32_e64 v19, s[0:1], 0, v17, s[0:1]
	v_add_co_u32_e64 v20, s[0:1], s5, v16
	s_add_u32 s2, s2, 0x18000
	s_nop 0
	v_addc_co_u32_e64 v21, s[0:1], 0, v17, s[0:1]
	v_add_co_u32_e64 v16, s[0:1], s6, v16
	s_addc_u32 s3, s3, 0
	s_nop 0
	v_addc_co_u32_e64 v17, s[0:1], 0, v17, s[0:1]
	global_load_dword v54, v[18:19], off
	global_load_dword v56, v[20:21], off
	global_load_dword v58, v[16:17], off
	ds_read_b128 v[16:19], v5
	ds_read_b128 v[20:23], v5 offset:4096
	ds_read_b128 v[24:27], v5 offset:8192
	ds_read_b128 v[28:31], v5 offset:12288
	v_add_u32_e32 v5, 16, v5
	s_waitcnt lgkmcnt(3)
	v_mov_b32_e32 v41, v16
	s_waitcnt lgkmcnt(2)
	v_mov_b32_e32 v40, v20
	s_waitcnt lgkmcnt(1)
	v_mov_b32_e32 v43, v24
	s_waitcnt lgkmcnt(0)
	v_mov_b32_e32 v42, v28
	v_mov_b32_e32 v16, v21
	v_mov_b32_e32 v24, v29
	v_mov_b32_e32 v20, v22
	v_mov_b32_e32 v21, v18
	v_mov_b32_e32 v28, v30
	v_mov_b32_e32 v29, v26
	v_mov_b32_e32 v18, v23
	v_mov_b32_e32 v26, v31
	s_waitcnt vmcnt(12)
	v_pk_fma_f32 v[10:11], v[60:61], v[40:41], v[10:11] op_sel_hi:[0,1,1]
	v_pk_fma_f32 v[8:9], v[60:61], v[42:43], v[8:9] op_sel_hi:[0,1,1]
	v_pk_fma_f32 v[10:11], v[62:63], v[16:17], v[10:11] op_sel_hi:[0,1,1]
	v_pk_fma_f32 v[8:9], v[62:63], v[24:25], v[8:9] op_sel_hi:[0,1,1]
	v_pk_fma_f32 v[10:11], v[64:65], v[20:21], v[10:11] op_sel_hi:[0,1,1]
	v_pk_fma_f32 v[8:9], v[64:65], v[28:29], v[8:9] op_sel_hi:[0,1,1]
	v_pk_fma_f32 v[10:11], v[66:67], v[18:19], v[10:11] op_sel_hi:[0,1,1]
	v_pk_fma_f32 v[8:9], v[66:67], v[26:27], v[8:9] op_sel_hi:[0,1,1]
	v_lshl_add_u64 v[16:17], v[6:7], 0, s[2:3]
	v_add_co_u32_e64 v18, s[0:1], s4, v16
	global_load_dword v60, v[16:17], off
	s_nop 0
	v_addc_co_u32_e64 v19, s[0:1], 0, v17, s[0:1]
	v_add_co_u32_e64 v20, s[0:1], s5, v16
	s_add_u32 s2, s2, 0x18000
	s_nop 0
	v_addc_co_u32_e64 v21, s[0:1], 0, v17, s[0:1]
	v_add_co_u32_e64 v16, s[0:1], s6, v16
	s_addc_u32 s3, s3, 0
	s_nop 0
	v_addc_co_u32_e64 v17, s[0:1], 0, v17, s[0:1]
	global_load_dword v62, v[18:19], off
	global_load_dword v64, v[20:21], off
	global_load_dword v66, v[16:17], off
	s_cmp_eq_u32 s2, 0x300000
	s_cbranch_scc0 .Lada_loop
; template <int PART>
; __device__ __forceinline__ void prologue(const Params& p, unsigned char* lds) {
;     ...
;         for (int k = kp * 128; k < kp * 128 + 128; ++k) { const float wv = w[(size_t)k * 6144]; a0 += sc[k] * wv; a1 += sc[1024 + k] * wv; a2 += sc[2048 + k] * wv; a3 += sc[3072 + k] * wv; }
;         red[(kp * 4 + 0) * 64 + (tid & 63)] = a0; red[(kp * 4 + 1) * 64 + (tid & 63)] = a1; red[(kp * 4 + 2) * 64 + (tid & 63)] = a2; red[(kp * 4 + 3) * 64 + (tid & 63)] = a3;
;         __syncthreads();
;         if (tid < 256) { const int b = tid >> 6, c = tid & 63; float s = 0.f;
; #pragma unroll
;             for (int q = 0; q < 8; ++q) s += red[(q * 4 + b) * 64 + c];
;             const int nn = (u % 96) * 64 + c;
;             ((float*)(ws + WS_MOD))[(l * 4 + b) * 6144 + nn] = s + p.in[I_ADAB][l * 6144 + nn]; }
	ds_read_b128 v[16:19], v5
	ds_read_b128 v[20:23], v5 offset:4096
	ds_read_b128 v[24:27], v5 offset:8192
	ds_read_b128 v[28:31], v5 offset:12288
	v_add_u32_e32 v5, 16, v5
	s_waitcnt lgkmcnt(3)
	v_mov_b32_e32 v41, v16
	s_waitcnt lgkmcnt(2)
	v_mov_b32_e32 v40, v20
	s_waitcnt lgkmcnt(1)
	v_mov_b32_e32 v43, v24
	s_waitcnt lgkmcnt(0)
	v_mov_b32_e32 v42, v28
	v_mov_b32_e32 v16, v21
	v_mov_b32_e32 v24, v29
	v_mov_b32_e32 v20, v22
	v_mov_b32_e32 v21, v18
	v_mov_b32_e32 v28, v30
	v_mov_b32_e32 v29, v26
	v_mov_b32_e32 v18, v23
	v_mov_b32_e32 v26, v31
	s_waitcnt vmcnt(12)
	v_pk_fma_f32 v[10:11], v[32:33], v[40:41], v[10:11] op_sel_hi:[0,1,1]
	v_pk_fma_f32 v[8:9], v[32:33], v[42:43], v[8:9] op_sel_hi:[0,1,1]
	v_pk_fma_f32 v[10:11], v[34:35], v[16:17], v[10:11] op_sel_hi:[0,1,1]
	v_pk_fma_f32 v[8:9], v[34:35], v[24:25], v[8:9] op_sel_hi:[0,1,1]
	v_pk_fma_f32 v[10:11], v[36:37], v[20:21], v[10:11] op_sel_hi:[0,1,1]
	v_pk_fma_f32 v[8:9], v[36:37], v[28:29], v[8:9] op_sel_hi:[0,1,1]
	v_pk_fma_f32 v[10:11], v[38:39], v[18:19], v[10:11] op_sel_hi:[0,1,1]
	v_pk_fma_f32 v[8:9], v[38:39], v[26:27], v[8:9] op_sel_hi:[0,1,1]
	ds_read_b128 v[16:19], v5
	ds_read_b128 v[20:23], v5 offset:4096
	ds_read_b128 v[24:27], v5 offset:8192
	ds_read_b128 v[28:31], v5 offset:12288
	v_add_u32_e32 v5, 16, v5
	s_waitcnt lgkmcnt(3)
	v_mov_b32_e32 v41, v16
	s_waitcnt lgkmcnt(2)
	v_mov_b32_e32 v40, v20
	s_waitcnt lgkmcnt(1)
	v_mov_b32_e32 v43, v24
	s_waitcnt lgkmcnt(0)
	v_mov_b32_e32 v42, v28
	v_mov_b32_e32 v16, v21
	v_mov_b32_e32 v24, v29
	v_mov_b32_e32 v20, v22
	v_mov_b32_e32 v21, v18
	v_mov_b32_e32 v28, v30
	v_mov_b32_e32 v29, v26
	v_mov_b32_e32 v18, v23
	v_mov_b32_e32 v26, v31
	s_waitcnt vmcnt(8)
	v_pk_fma_f32 v[10:11], v[44:45], v[40:41], v[10:11] op_sel_hi:[0,1,1]
	v_pk_fma_f32 v[8:9], v[44:45], v[42:43], v[8:9] op_sel_hi:[0,1,1]
	v_pk_fma_f32 v[10:11], v[46:47], v[16:17], v[10:11] op_sel_hi:[0,1,1]
	v_pk_fma_f32 v[8:9], v[46:47], v[24:25], v[8:9] op_sel_hi:[0,1,1]
	v_pk_fma_f32 v[10:11], v[48:49], v[20:21], v[10:11] op_sel_hi:[0,1,1]
	v_pk_fma_f32 v[8:9], v[48:49], v[28:29], v[8:9] op_sel_hi:[0,1,1]
	v_pk_fma_f32 v[10:11], v[50:51], v[18:19], v[10:11] op_sel_hi:[0,1,1]
	v_pk_fma_f32 v[8:9], v[50:51], v[26:27], v[8:9] op_sel_hi:[0,1,1]
	ds_read_b128 v[16:19], v5
	ds_read_b128 v[20:23], v5 offset:4096
	ds_read_b128 v[24:27], v5 offset:8192
	ds_read_b128 v[28:31], v5 offset:12288
	v_add_u32_e32 v5, 16, v5
	s_waitcnt lgkmcnt(3)
	v_mov_b32_e32 v41, v16
	s_waitcnt lgkmcnt(2)
	v_mov_b32_e32 v40, v20
	s_waitcnt lgkmcnt(1)
	v_mov_b32_e32 v43, v24
	s_waitcnt lgkmcnt(0)
	v_mov_b32_e32 v42, v28
	v_mov_b32_e32 v16, v21
	v_mov_b32_e32 v24, v29
	v_mov_b32_e32 v20, v22
	v_mov_b32_e32 v21, v18
	v_mov_b32_e32 v28, v30
	v_mov_b32_e32 v29, v26
	v_mov_b32_e32 v18, v23
	v_mov_b32_e32 v26, v31
	s_waitcnt vmcnt(4)
	v_pk_fma_f32 v[10:11], v[52:53], v[40:41], v[10:11] op_sel_hi:[0,1,1]
	v_pk_fma_f32 v[8:9], v[52:53], v[42:43], v[8:9] op_sel_hi:[0,1,1]
	v_pk_fma_f32 v[10:11], v[54:55], v[16:17], v[10:11] op_sel_hi:[0,1,1]
	v_pk_fma_f32 v[8:9], v[54:55], v[24:25], v[8:9] op_sel_hi:[0,1,1]
	v_pk_fma_f32 v[10:11], v[56:57], v[20:21], v[10:11] op_sel_hi:[0,1,1]
	v_pk_fma_f32 v[8:9], v[56:57], v[28:29], v[8:9] op_sel_hi:[0,1,1]
	v_pk_fma_f32 v[10:11], v[58:59], v[18:19], v[10:11] op_sel_hi:[0,1,1]
	v_pk_fma_f32 v[8:9], v[58:59], v[26:27], v[8:9] op_sel_hi:[0,1,1]
	ds_read_b128 v[16:19], v5
	ds_read_b128 v[20:23], v5 offset:4096
	ds_read_b128 v[24:27], v5 offset:8192
	ds_read_b128 v[28:31], v5 offset:12288
	v_add_u32_e32 v5, 16, v5
	s_waitcnt lgkmcnt(3)
	v_mov_b32_e32 v41, v16
	s_waitcnt lgkmcnt(2)
	v_mov_b32_e32 v40, v20
	s_waitcnt lgkmcnt(1)
	v_mov_b32_e32 v43, v24
	s_waitcnt lgkmcnt(0)
	v_mov_b32_e32 v42, v28
	v_mov_b32_e32 v16, v21
	v_mov_b32_e32 v24, v29
	v_mov_b32_e32 v20, v22
	v_mov_b32_e32 v21, v18
	v_mov_b32_e32 v28, v30
	v_mov_b32_e32 v29, v26
	v_mov_b32_e32 v18, v23
	v_mov_b32_e32 v26, v31
	s_waitcnt vmcnt(0)
	v_pk_fma_f32 v[10:11], v[60:61], v[40:41], v[10:11] op_sel_hi:[0,1,1]
	v_pk_fma_f32 v[8:9], v[60:61], v[42:43], v[8:9] op_sel_hi:[0,1,1]
	v_pk_fma_f32 v[10:11], v[62:63], v[16:17], v[10:11] op_sel_hi:[0,1,1]
	v_pk_fma_f32 v[8:9], v[62:63], v[24:25], v[8:9] op_sel_hi:[0,1,1]
	v_pk_fma_f32 v[10:11], v[64:65], v[20:21], v[10:11] op_sel_hi:[0,1,1]
	v_pk_fma_f32 v[8:9], v[64:65], v[28:29], v[8:9] op_sel_hi:[0,1,1]
	v_pk_fma_f32 v[10:11], v[66:67], v[18:19], v[10:11] op_sel_hi:[0,1,1]
	v_pk_fma_f32 v[8:9], v[66:67], v[26:27], v[8:9] op_sel_hi:[0,1,1]
	ds_write2st64_b32 v12, v11, v10 offset0:64 offset1:65
	ds_write2st64_b32 v12, v9, v8 offset0:66 offset1:67
	s_waitcnt lgkmcnt(0)
	s_barrier
	s_and_saveexec_b64 s[0:1], vcc
	s_cbranch_execz .LBB0_76
	s_mul_i32 s2, s9, 0x1800
	v_add_u32_e32 v6, s2, v4
	v_readlane_b32 s12, v246, 16
	v_ashrrev_i32_e32 v7, 31, v6
	v_readlane_b32 s18, v246, 22
	v_readlane_b32 s19, v246, 23
	v_lshl_or_b32 v5, s9, 2, v222
	v_mad_u64_u32 v[4:5], s[2:3], v5, s7, v[4:5]
	v_lshl_add_u64 v[6:7], v[6:7], 2, s[18:19]
	global_load_dword v18, v[6:7], off
	ds_read2st64_b32 v[6:7], v13 offset0:64 offset1:68
	ds_read2st64_b32 v[8:9], v13 offset0:72 offset1:76
	ds_read2st64_b32 v[10:11], v13 offset0:80 offset1:84
	ds_read2st64_b32 v[16:17], v13 offset0:88 offset1:92
	v_ashrrev_i32_e32 v5, 31, v4
	s_waitcnt lgkmcnt(3)
	v_add_f32_e32 v6, 0, v6
	v_add_f32_e32 v6, v6, v7
	s_waitcnt lgkmcnt(2)
	v_add_f32_e32 v6, v6, v8
	v_add_f32_e32 v6, v6, v9
	s_waitcnt lgkmcnt(1)
	v_add_f32_e32 v6, v6, v10
	v_add_f32_e32 v6, v6, v11
	s_waitcnt lgkmcnt(0)
	v_add_f32_e32 v6, v6, v16
	v_add_f32_e32 v6, v6, v17
	v_lshl_add_u64 v[4:5], v[4:5], 2, s[96:97]
	v_readlane_b32 s13, v246, 17
	v_readlane_b32 s14, v246, 18
	v_readlane_b32 s15, v246, 19
	v_readlane_b32 s16, v246, 20
	v_readlane_b32 s17, v246, 21
	v_readlane_b32 s20, v246, 24
	v_readlane_b32 s21, v246, 25
	v_readlane_b32 s22, v246, 26
	v_readlane_b32 s23, v246, 27
	v_readlane_b32 s24, v246, 28
	v_readlane_b32 s25, v246, 29
	v_readlane_b32 s26, v246, 30
	v_readlane_b32 s27, v246, 31
	s_waitcnt vmcnt(0)
	v_add_f32_e32 v6, v6, v18
	global_store_dword v[4:5], v6, off
	s_branch .LBB0_76

; __device__ __forceinline__ void lru_wave_unit(const Params& p, int l, bf16_t* Z, LAS unsigned char* ldsw, int b, int ch, int n, int final) {
;     ...
;         for (int i = 0; i < 8; ++i) { const int t = tr + 8 * i; float acc[8];
; #pragma unroll
;             for (int e = 0; e < 8; ++e) acc[e] = cb[e];
; #pragma unroll
;             for (int k = 0; k < 4; ++k) { const int tt = t0 + t - 3 + k;
;                 if (tt >= 0) { const u32x4 raw = *(const u32x4*)(Z + (rowb + tt) * ZP + ZC_LRUX + chn);
;                     const float x[8] = {bflo(raw.x), bfhi(raw.x), bflo(raw.y), bfhi(raw.y), bflo(raw.z), bfhi(raw.z), bflo(raw.w), bfhi(raw.w)};
; #pragma unroll
;                     for (int e = 0; e < 8; ++e) acc[e] += x[e] * cw[k][e]; } }
.LBB0_375:
	v_add_u32_e32 v66, -2, v40
	v_cmp_lt_i32_e32 vcc, -1, v66
	v_mov_b64_e32 v[62:63], v[10:11]
	s_waitcnt vmcnt(3)
	v_mov_b32_e32 v56, v24
	v_mov_b32_e32 v57, v25
	v_mov_b32_e32 v22, v26
	v_mov_b32_e32 v23, v27
	v_mov_b32_e32 v58, v8
	v_mov_b32_e32 v59, v9
	v_mov_b32_e32 v60, v10
	v_mov_b32_e32 v61, v11
	v_cmp_lt_i32_e32 vcc, -1, v66
	s_and_saveexec_b64 s[28:29], vcc
	v_mov_b32_e32 v198, v66
	v_mov_b32_e32 v199, v67
	v_lshl_add_u64 v[198:199], s[6:7], 0, v[198:199]
	v_mad_u64_u32 v[200:201], s[64:65], v198, s37, v[42:43]
	v_mad_i32_i24 v201, v199, s37, v201
	global_load_dwordx4 v[200:203], v[200:201], off offset:3072
	s_or_b64 exec, exec, s[28:29]
	v_cmp_lt_i32_e32 vcc, -2, v66
	s_and_saveexec_b64 s[28:29], vcc
	v_add_u32_e32 v198, -1, v40
	v_mov_b32_e32 v199, v67
	v_lshl_add_u64 v[198:199], s[6:7], 0, v[198:199]
	v_mad_u64_u32 v[204:205], s[64:65], v198, s37, v[42:43]
	v_mad_i32_i24 v205, v199, s37, v205
	global_load_dwordx4 v[204:207], v[204:205], off offset:3072
	s_or_b64 exec, exec, s[28:29]
	v_cmp_lt_i32_e32 vcc, -3, v66
	s_and_saveexec_b64 s[28:29], vcc
	v_mov_b32_e32 v198, v40
	v_mov_b32_e32 v199, v67
	v_lshl_add_u64 v[198:199], s[6:7], 0, v[198:199]
	v_mad_u64_u32 v[208:209], s[64:65], v198, s37, v[42:43]
	v_mad_i32_i24 v209, v199, s37, v209
	global_load_dwordx4 v[208:211], v[208:209], off offset:3072
	s_or_b64 exec, exec, s[28:29]
	v_cmp_lt_i32_e32 vcc, -1, v66
	s_and_saveexec_b64 s[28:29], vcc
	s_cbranch_execnz .LBB0_378
	s_or_b64 exec, exec, s[28:29]
	v_cmp_lt_i32_e32 vcc, -2, v66
	s_and_saveexec_b64 s[28:29], vcc
	s_cbranch_execnz .LBB0_379

; __device__ __forceinline__ void lru_wave_unit(const Params& p, int l, bf16_t* Z, LAS unsigned char* ldsw, int b, int ch, int n, int final) {
;     ...
;             for (int k = 0; k < 4; ++k) { const int tt = t0 + t - 3 + k;
;                 if (tt >= 0) { const u32x4 raw = *(const u32x4*)(Z + (rowb + tt) * ZP + ZC_LRUX + chn);
;                     const float x[8] = {bflo(raw.x), bfhi(raw.x), bflo(raw.y), bfhi(raw.y), bflo(raw.z), bfhi(raw.z), bflo(raw.w), bfhi(raw.w)};
; #pragma unroll
;                     for (int e = 0; e < 8; ++e) acc[e] += x[e] * cw[k][e]; } }
.LBB0_378:
	v_lshl_add_u64 v[22:23], s[6:7], 0, v[66:67]
	v_mad_u64_u32 v[56:57], s[64:65], v22, s37, v[42:43]
	v_mad_i32_i24 v57, v23, s37, v57
	s_waitcnt vmcnt(2)
	v_mov_b64_e32 v[56:57], v[200:201]
	v_mov_b64_e32 v[58:59], v[202:203]
	v_lshlrev_b32_e32 v62, 16, v58
	v_and_b32_e32 v63, 0xffff0000, v58
	v_lshlrev_b32_e32 v78, 16, v59
	v_and_b32_e32 v79, 0xffff0000, v59
	v_lshlrev_b32_e32 v22, 16, v56
	v_and_b32_e32 v23, 0xffff0000, v56
	v_lshlrev_b32_e32 v60, 16, v57
	v_and_b32_e32 v61, 0xffff0000, v57
	v_pk_fma_f32 v[58:59], v[12:13], v[62:63], v[8:9]
	v_pk_fma_f32 v[62:63], v[14:15], v[78:79], v[10:11]
	v_pk_fma_f32 v[56:57], v[28:29], v[22:23], v[24:25]
	v_pk_fma_f32 v[22:23], v[30:31], v[60:61], v[26:27]
	v_mov_b32_e32 v60, v62
	v_mov_b32_e32 v61, v63
	s_or_b64 exec, exec, s[28:29]
	v_cmp_lt_i32_e32 vcc, -2, v66
	s_and_saveexec_b64 s[28:29], vcc
	s_cbranch_execz .LBB0_377
.LBB0_379:
	v_add_u32_e32 v60, -1, v40
	v_mov_b32_e32 v61, v67
	v_lshl_add_u64 v[60:61], s[6:7], 0, v[60:61]
	v_mad_u64_u32 v[78:79], s[64:65], v60, s37, v[42:43]
	v_mad_i32_i24 v79, v61, s37, v79
	s_waitcnt vmcnt(1)
	v_mov_b64_e32 v[78:79], v[204:205]
	v_mov_b64_e32 v[80:81], v[206:207]
	v_lshlrev_b32_e32 v60, 16, v78
	v_and_b32_e32 v61, 0xffff0000, v78
	v_lshlrev_b32_e32 v78, 16, v79
	v_and_b32_e32 v79, 0xffff0000, v79
	v_lshlrev_b32_e32 v102, 16, v80
	v_and_b32_e32 v103, 0xffff0000, v80
	v_lshlrev_b32_e32 v80, 16, v81
	v_and_b32_e32 v81, 0xffff0000, v81
	v_pk_fma_f32 v[56:57], v[36:37], v[60:61], v[56:57]
	v_pk_fma_f32 v[22:23], v[38:39], v[78:79], v[22:23]
	v_pk_fma_f32 v[58:59], v[32:33], v[102:103], v[58:59]
	v_pk_fma_f32 v[60:61], v[34:35], v[80:81], v[62:63]
	s_or_b64 exec, exec, s[28:29]
	v_cmp_lt_i32_e32 vcc, -3, v66
	s_and_saveexec_b64 s[28:29], vcc
	s_cbranch_execz .LBB0_374
.LBB0_380:
	v_mov_b32_e32 v41, v67
	v_lshl_add_u64 v[62:63], s[6:7], 0, v[40:41]
	v_mad_u64_u32 v[78:79], s[64:65], v62, s37, v[42:43]
	v_mad_i32_i24 v79, v63, s37, v79
	s_waitcnt vmcnt(0)
	v_mov_b64_e32 v[78:79], v[208:209]
	v_mov_b64_e32 v[80:81], v[210:211]
	v_lshlrev_b32_e32 v62, 16, v78
	v_and_b32_e32 v63, 0xffff0000, v78
	v_lshlrev_b32_e32 v78, 16, v79
	v_and_b32_e32 v79, 0xffff0000, v79
	v_lshlrev_b32_e32 v102, 16, v80
	v_and_b32_e32 v103, 0xffff0000, v80
	v_lshlrev_b32_e32 v80, 16, v81
	v_and_b32_e32 v81, 0xffff0000, v81
	v_pk_fma_f32 v[56:57], v[0:1], v[62:63], v[56:57]
	v_pk_fma_f32 v[22:23], v[2:3], v[78:79], v[22:23]
	v_pk_fma_f32 v[58:59], v[16:17], v[102:103], v[58:59]
	v_pk_fma_f32 v[60:61], v[18:19], v[80:81], v[60:61]
	s_branch .LBB0_374

; __device__ __forceinline__ void lru_wave_unit(const Params& p, int l, bf16_t* Z, LAS unsigned char* ldsw, int b, int ch, int n, int final) {
;     ...
;         for (int i = 0; i < 8; ++i) { const int t = tr + 8 * i; float acc[8];
; #pragma unroll
;             for (int e = 0; e < 8; ++e) acc[e] = cb[e];
; #pragma unroll
;             for (int k = 0; k < 4; ++k) { const int tt = t0 + t - 3 + k;
;                 if (tt >= 0) { const u32x4 raw = *(const u32x4*)(Z + (rowb + tt) * ZP + ZC_LRUX + chn);
;                     const float x[8] = {bflo(raw.x), bfhi(raw.x), bflo(raw.y), bfhi(raw.y), bflo(raw.z), bfhi(raw.z), bflo(raw.w), bfhi(raw.w)};
; #pragma unroll
;                     for (int e = 0; e < 8; ++e) acc[e] += x[e] * cw[k][e]; } }
.LBB0_538:
	v_add_u32_e32 v74, -2, v48
	v_cmp_lt_i32_e32 vcc, -1, v74
	v_mov_b64_e32 v[40:41], v[10:11]
	s_waitcnt vmcnt(3)
	v_mov_b32_e32 v64, v24
	v_mov_b32_e32 v65, v25
	v_mov_b32_e32 v22, v26
	v_mov_b32_e32 v23, v27
	v_mov_b32_e32 v66, v8
	v_mov_b32_e32 v67, v9
	v_mov_b32_e32 v68, v10
	v_mov_b32_e32 v69, v11
	v_cmp_lt_i32_e32 vcc, -1, v74
	s_and_saveexec_b64 s[6:7], vcc
	v_mov_b32_e32 v198, v74
	v_mov_b32_e32 v199, v75
	v_lshl_add_u64 v[198:199], s[20:21], 0, v[198:199]
	v_mad_u64_u32 v[200:201], s[72:73], v198, s28, v[50:51]
	v_mad_i32_i24 v201, v199, s28, v201
	global_load_dwordx4 v[200:203], v[200:201], off offset:3072
	s_or_b64 exec, exec, s[6:7]
	v_cmp_lt_i32_e32 vcc, -2, v74
	s_and_saveexec_b64 s[6:7], vcc
	v_add_u32_e32 v198, -1, v48
	v_mov_b32_e32 v199, v75
	v_lshl_add_u64 v[198:199], s[20:21], 0, v[198:199]
	v_mad_u64_u32 v[204:205], s[72:73], v198, s28, v[50:51]
	v_mad_i32_i24 v205, v199, s28, v205
	global_load_dwordx4 v[204:207], v[204:205], off offset:3072
	s_or_b64 exec, exec, s[6:7]
	v_cmp_lt_i32_e32 vcc, -3, v74
	s_and_saveexec_b64 s[6:7], vcc
	v_mov_b32_e32 v198, v48
	v_mov_b32_e32 v199, v75
	v_lshl_add_u64 v[198:199], s[20:21], 0, v[198:199]
	v_mad_u64_u32 v[208:209], s[72:73], v198, s28, v[50:51]
	v_mad_i32_i24 v209, v199, s28, v209
	global_load_dwordx4 v[208:211], v[208:209], off offset:3072
	s_or_b64 exec, exec, s[6:7]
	v_cmp_lt_i32_e32 vcc, -1, v74
	s_and_saveexec_b64 s[6:7], vcc
	s_cbranch_execnz .LBB0_541
	s_or_b64 exec, exec, s[6:7]
	v_cmp_lt_i32_e32 vcc, -2, v74
	s_and_saveexec_b64 s[6:7], vcc
	s_cbranch_execnz .LBB0_542

; __device__ __forceinline__ void lru_wave_unit(const Params& p, int l, bf16_t* Z, LAS unsigned char* ldsw, int b, int ch, int n, int final) {
;     ...
;             for (int k = 0; k < 4; ++k) { const int tt = t0 + t - 3 + k;
;                 if (tt >= 0) { const u32x4 raw = *(const u32x4*)(Z + (rowb + tt) * ZP + ZC_LRUX + chn);
;                     const float x[8] = {bflo(raw.x), bfhi(raw.x), bflo(raw.y), bfhi(raw.y), bflo(raw.z), bfhi(raw.z), bflo(raw.w), bfhi(raw.w)};
; #pragma unroll
;                     for (int e = 0; e < 8; ++e) acc[e] += x[e] * cw[k][e]; } }
.LBB0_541:
	v_lshl_add_u64 v[22:23], s[20:21], 0, v[74:75]
	v_mad_u64_u32 v[40:41], s[72:73], v22, s28, v[50:51]
	v_mad_i32_i24 v41, v23, s28, v41
	s_waitcnt vmcnt(2)
	v_mov_b64_e32 v[40:41], v[200:201]
	v_mov_b64_e32 v[42:43], v[202:203]
	v_lshlrev_b32_e32 v22, 16, v40
	v_and_b32_e32 v23, 0xffff0000, v40
	v_lshlrev_b32_e32 v40, 16, v41
	v_and_b32_e32 v41, 0xffff0000, v41
	v_lshlrev_b32_e32 v44, 16, v42
	v_and_b32_e32 v45, 0xffff0000, v42
	v_lshlrev_b32_e32 v42, 16, v43
	v_and_b32_e32 v43, 0xffff0000, v43
	v_pk_fma_f32 v[64:65], v[28:29], v[22:23], v[24:25]
	v_pk_fma_f32 v[22:23], v[30:31], v[40:41], v[26:27]
	v_pk_fma_f32 v[40:41], v[14:15], v[42:43], v[10:11]
	v_pk_fma_f32 v[66:67], v[12:13], v[44:45], v[8:9]
	v_mov_b32_e32 v68, v40
	v_mov_b32_e32 v69, v41
	s_or_b64 exec, exec, s[6:7]
	v_cmp_lt_i32_e32 vcc, -2, v74
	s_and_saveexec_b64 s[6:7], vcc
	s_cbranch_execz .LBB0_540
.LBB0_542:
	v_add_u32_e32 v42, -1, v48
	v_mov_b32_e32 v43, v75
	v_lshl_add_u64 v[42:43], s[20:21], 0, v[42:43]
	v_mad_u64_u32 v[44:45], s[72:73], v42, s28, v[50:51]
	v_mad_i32_i24 v45, v43, s28, v45
	s_waitcnt vmcnt(1)
	v_mov_b64_e32 v[42:43], v[204:205]
	v_mov_b64_e32 v[44:45], v[206:207]
	v_lshlrev_b32_e32 v46, 16, v42
	v_and_b32_e32 v47, 0xffff0000, v42
	v_lshlrev_b32_e32 v42, 16, v43
	v_and_b32_e32 v43, 0xffff0000, v43
	v_pk_fma_f32 v[22:23], v[38:39], v[42:43], v[22:23]
	v_lshlrev_b32_e32 v42, 16, v44
	v_and_b32_e32 v43, 0xffff0000, v44
	v_pk_fma_f32 v[66:67], v[32:33], v[42:43], v[66:67]
	v_lshlrev_b32_e32 v42, 16, v45
	v_and_b32_e32 v43, 0xffff0000, v45
	v_pk_fma_f32 v[64:65], v[36:37], v[46:47], v[64:65]
	v_pk_fma_f32 v[68:69], v[34:35], v[42:43], v[40:41]
	s_or_b64 exec, exec, s[6:7]
	v_cmp_lt_i32_e32 vcc, -3, v74
	s_and_saveexec_b64 s[6:7], vcc
	s_cbranch_execz .LBB0_537
.LBB0_543:
	v_mov_b32_e32 v49, v75
	v_lshl_add_u64 v[40:41], s[20:21], 0, v[48:49]
	v_mad_u64_u32 v[42:43], s[72:73], v40, s28, v[50:51]
	v_mad_i32_i24 v43, v41, s28, v43
	s_waitcnt vmcnt(0)
	v_mov_b64_e32 v[40:41], v[208:209]
	v_mov_b64_e32 v[42:43], v[210:211]
	v_lshlrev_b32_e32 v44, 16, v40
	v_and_b32_e32 v45, 0xffff0000, v40
	v_lshlrev_b32_e32 v40, 16, v41
	v_and_b32_e32 v41, 0xffff0000, v41
	v_pk_fma_f32 v[22:23], v[2:3], v[40:41], v[22:23]
	v_lshlrev_b32_e32 v40, 16, v42
	v_and_b32_e32 v41, 0xffff0000, v42
	v_pk_fma_f32 v[66:67], v[16:17], v[40:41], v[66:67]
	v_lshlrev_b32_e32 v40, 16, v43
	v_and_b32_e32 v41, 0xffff0000, v43
	v_pk_fma_f32 v[64:65], v[0:1], v[44:45], v[64:65]
	v_pk_fma_f32 v[68:69], v[18:19], v[40:41], v[68:69]
	s_branch .LBB0_537

; __device__ __forceinline__ void lru_wave_unit(const Params& p, int l, bf16_t* Z, LAS unsigned char* ldsw, int b, int ch, int n, int final) {
;     ...
;         for (int i = 0; i < 8; ++i) { const int t = tr + 8 * i; float acc[8];
; #pragma unroll
;             for (int e = 0; e < 8; ++e) acc[e] = cb[e];
; #pragma unroll
;             for (int k = 0; k < 4; ++k) { const int tt = t0 + t - 3 + k;
;                 if (tt >= 0) { const u32x4 raw = *(const u32x4*)(Z + (rowb + tt) * ZP + ZC_LRUX + chn);
;                     const float x[8] = {bflo(raw.x), bfhi(raw.x), bflo(raw.y), bfhi(raw.y), bflo(raw.z), bfhi(raw.z), bflo(raw.w), bfhi(raw.w)};
; #pragma unroll
;                     for (int e = 0; e < 8; ++e) acc[e] += x[e] * cw[k][e]; } }
.LBB0_1831:
	v_add_u32_e32 v66, -2, v40
	v_cmp_lt_i32_e32 vcc, -1, v66
	v_mov_b64_e32 v[62:63], v[2:3]
	v_mov_b32_e32 v56, v4
	v_mov_b32_e32 v57, v5
	v_mov_b32_e32 v22, v6
	v_mov_b32_e32 v23, v7
	v_mov_b32_e32 v58, v0
	v_mov_b32_e32 v59, v1
	v_mov_b32_e32 v60, v2
	v_mov_b32_e32 v61, v3
	v_cmp_lt_i32_e32 vcc, -1, v66
	s_and_saveexec_b64 s[36:37], vcc
	v_mov_b32_e32 v198, v66
	v_mov_b32_e32 v199, v67
	v_lshl_add_u64 v[198:199], s[6:7], 0, v[198:199]
	v_mad_u64_u32 v[200:201], s[62:63], v198, s41, v[42:43]
	v_mad_i32_i24 v201, v199, s41, v201
	global_load_dwordx4 v[200:203], v[200:201], off offset:3072
	s_or_b64 exec, exec, s[36:37]
	v_cmp_lt_i32_e32 vcc, -2, v66
	s_and_saveexec_b64 s[36:37], vcc
	v_add_u32_e32 v198, -1, v40
	v_mov_b32_e32 v199, v67
	v_lshl_add_u64 v[198:199], s[6:7], 0, v[198:199]
	v_mad_u64_u32 v[204:205], s[62:63], v198, s41, v[42:43]
	v_mad_i32_i24 v205, v199, s41, v205
	global_load_dwordx4 v[204:207], v[204:205], off offset:3072
	s_or_b64 exec, exec, s[36:37]
	v_cmp_lt_i32_e32 vcc, -3, v66
	s_and_saveexec_b64 s[36:37], vcc
	v_mov_b32_e32 v198, v40
	v_mov_b32_e32 v199, v67
	v_lshl_add_u64 v[198:199], s[6:7], 0, v[198:199]
	v_mad_u64_u32 v[208:209], s[62:63], v198, s41, v[42:43]
	v_mad_i32_i24 v209, v199, s41, v209
	global_load_dwordx4 v[208:211], v[208:209], off offset:3072
	s_or_b64 exec, exec, s[36:37]
	v_cmp_lt_i32_e32 vcc, -1, v66
	s_and_saveexec_b64 s[36:37], vcc
	s_cbranch_execnz .LBB0_1834
	s_or_b64 exec, exec, s[36:37]
	v_cmp_lt_i32_e32 vcc, -2, v66
	s_and_saveexec_b64 s[36:37], vcc
	s_cbranch_execnz .LBB0_1835

; __device__ __forceinline__ void lru_wave_unit(const Params& p, int l, bf16_t* Z, LAS unsigned char* ldsw, int b, int ch, int n, int final) {
;     ...
;             for (int k = 0; k < 4; ++k) { const int tt = t0 + t - 3 + k;
;                 if (tt >= 0) { const u32x4 raw = *(const u32x4*)(Z + (rowb + tt) * ZP + ZC_LRUX + chn);
;                     const float x[8] = {bflo(raw.x), bfhi(raw.x), bflo(raw.y), bfhi(raw.y), bflo(raw.z), bfhi(raw.z), bflo(raw.w), bfhi(raw.w)};
; #pragma unroll
;                     for (int e = 0; e < 8; ++e) acc[e] += x[e] * cw[k][e]; } }
.LBB0_1834:
	v_lshl_add_u64 v[22:23], s[6:7], 0, v[66:67]
	v_mad_u64_u32 v[56:57], s[62:63], v22, s41, v[42:43]
	v_mad_i32_i24 v57, v23, s41, v57
	s_waitcnt vmcnt(2)
	v_mov_b64_e32 v[56:57], v[200:201]
	v_mov_b64_e32 v[58:59], v[202:203]
	v_lshlrev_b32_e32 v62, 16, v58
	v_and_b32_e32 v63, 0xffff0000, v58
	v_lshlrev_b32_e32 v78, 16, v59
	v_and_b32_e32 v79, 0xffff0000, v59
	v_lshlrev_b32_e32 v22, 16, v56
	v_and_b32_e32 v23, 0xffff0000, v56
	v_lshlrev_b32_e32 v60, 16, v57
	v_and_b32_e32 v61, 0xffff0000, v57
	v_pk_fma_f32 v[58:59], v[24:25], v[62:63], v[0:1]
	v_pk_fma_f32 v[62:63], v[26:27], v[78:79], v[2:3]
	v_pk_fma_f32 v[56:57], v[32:33], v[22:23], v[4:5]
	v_pk_fma_f32 v[22:23], v[34:35], v[60:61], v[6:7]
	v_mov_b32_e32 v60, v62
	v_mov_b32_e32 v61, v63
	s_or_b64 exec, exec, s[36:37]
	v_cmp_lt_i32_e32 vcc, -2, v66
	s_and_saveexec_b64 s[36:37], vcc
	s_cbranch_execz .LBB0_1833
.LBB0_1835:
	v_add_u32_e32 v60, -1, v40
	v_mov_b32_e32 v61, v67
	v_lshl_add_u64 v[60:61], s[6:7], 0, v[60:61]
	v_mad_u64_u32 v[78:79], s[62:63], v60, s41, v[42:43]
	v_mad_i32_i24 v79, v61, s41, v79
	s_waitcnt vmcnt(1)
	v_mov_b64_e32 v[78:79], v[204:205]
	v_mov_b64_e32 v[80:81], v[206:207]
	v_lshlrev_b32_e32 v60, 16, v78
	v_and_b32_e32 v61, 0xffff0000, v78
	v_lshlrev_b32_e32 v78, 16, v79
	v_and_b32_e32 v79, 0xffff0000, v79
	v_lshlrev_b32_e32 v106, 16, v80
	v_and_b32_e32 v107, 0xffff0000, v80
	v_lshlrev_b32_e32 v80, 16, v81
	v_and_b32_e32 v81, 0xffff0000, v81
	v_pk_fma_f32 v[56:57], v[12:13], v[60:61], v[56:57]
	v_pk_fma_f32 v[22:23], v[14:15], v[78:79], v[22:23]
	v_pk_fma_f32 v[58:59], v[28:29], v[106:107], v[58:59]
	v_pk_fma_f32 v[60:61], v[30:31], v[80:81], v[62:63]
	s_or_b64 exec, exec, s[36:37]
	v_cmp_lt_i32_e32 vcc, -3, v66
	s_and_saveexec_b64 s[36:37], vcc
	s_cbranch_execz .LBB0_1830
.LBB0_1836:
	v_mov_b32_e32 v41, v67
	v_lshl_add_u64 v[62:63], s[6:7], 0, v[40:41]
	v_mad_u64_u32 v[78:79], s[62:63], v62, s41, v[42:43]
	v_mad_i32_i24 v79, v63, s41, v79
	s_waitcnt vmcnt(0)
	v_mov_b64_e32 v[78:79], v[208:209]
	v_mov_b64_e32 v[80:81], v[210:211]
	v_lshlrev_b32_e32 v62, 16, v78
	v_and_b32_e32 v63, 0xffff0000, v78
	v_lshlrev_b32_e32 v78, 16, v79
	v_and_b32_e32 v79, 0xffff0000, v79
	v_lshlrev_b32_e32 v106, 16, v80
	v_and_b32_e32 v107, 0xffff0000, v80
	v_lshlrev_b32_e32 v80, 16, v81
	v_and_b32_e32 v81, 0xffff0000, v81
	v_pk_fma_f32 v[56:57], v[36:37], v[62:63], v[56:57]
	v_pk_fma_f32 v[22:23], v[38:39], v[78:79], v[22:23]
	v_pk_fma_f32 v[58:59], v[16:17], v[106:107], v[58:59]
	v_pk_fma_f32 v[60:61], v[18:19], v[80:81], v[60:61]
	s_branch .LBB0_1830

; __device__ __forceinline__ void lru_wave_unit(const Params& p, int l, bf16_t* Z, LAS unsigned char* ldsw, int b, int ch, int n, int final) {
;     ...
;         for (int i = 0; i < 8; ++i) { const int t = tr + 8 * i; float acc[8];
; #pragma unroll
;             for (int e = 0; e < 8; ++e) acc[e] = cb[e];
; #pragma unroll
;             for (int k = 0; k < 4; ++k) { const int tt = t0 + t - 3 + k;
;                 if (tt >= 0) { const u32x4 raw = *(const u32x4*)(Z + (rowb + tt) * ZP + ZC_LRUX + chn);
;                     const float x[8] = {bflo(raw.x), bfhi(raw.x), bflo(raw.y), bfhi(raw.y), bflo(raw.z), bfhi(raw.z), bflo(raw.w), bfhi(raw.w)};
; #pragma unroll
;                     for (int e = 0; e < 8; ++e) acc[e] += x[e] * cw[k][e]; } }
.LBB0_1949:
	v_add_u32_e32 v74, -2, v40
	v_cmp_lt_i32_e32 vcc, -1, v74
	v_mov_b64_e32 v[62:63], v[2:3]
	v_mov_b32_e32 v56, v4
	v_mov_b32_e32 v57, v5
	v_mov_b32_e32 v22, v6
	v_mov_b32_e32 v23, v7
	v_mov_b32_e32 v58, v0
	v_mov_b32_e32 v59, v1
	v_mov_b32_e32 v60, v2
	v_mov_b32_e32 v61, v3
	v_cmp_lt_i32_e32 vcc, -1, v74
	s_and_saveexec_b64 s[26:27], vcc
	v_mov_b32_e32 v198, v74
	v_mov_b32_e32 v199, v75
	v_lshl_add_u64 v[198:199], s[6:7], 0, v[198:199]
	v_mad_u64_u32 v[200:201], s[76:77], v198, s34, v[42:43]
	v_mad_i32_i24 v201, v199, s34, v201
	global_load_dwordx4 v[200:203], v[200:201], off offset:3072
	s_or_b64 exec, exec, s[26:27]
	v_cmp_lt_i32_e32 vcc, -2, v74
	s_and_saveexec_b64 s[26:27], vcc
	v_add_u32_e32 v198, -1, v40
	v_mov_b32_e32 v199, v75
	v_lshl_add_u64 v[198:199], s[6:7], 0, v[198:199]
	v_mad_u64_u32 v[204:205], s[76:77], v198, s34, v[42:43]
	v_mad_i32_i24 v205, v199, s34, v205
	global_load_dwordx4 v[204:207], v[204:205], off offset:3072
	s_or_b64 exec, exec, s[26:27]
	v_cmp_lt_i32_e32 vcc, -3, v74
	s_and_saveexec_b64 s[26:27], vcc
	v_mov_b32_e32 v198, v40
	v_mov_b32_e32 v199, v75
	v_lshl_add_u64 v[198:199], s[6:7], 0, v[198:199]
	v_mad_u64_u32 v[208:209], s[76:77], v198, s34, v[42:43]
	v_mad_i32_i24 v209, v199, s34, v209
	global_load_dwordx4 v[208:211], v[208:209], off offset:3072
	s_or_b64 exec, exec, s[26:27]
	v_cmp_lt_i32_e32 vcc, -1, v74
	s_and_saveexec_b64 s[26:27], vcc
	s_cbranch_execnz .LBB0_1952
	s_or_b64 exec, exec, s[26:27]
	v_cmp_lt_i32_e32 vcc, -2, v74
	s_and_saveexec_b64 s[26:27], vcc
	s_cbranch_execnz .LBB0_1953

; __device__ __forceinline__ void lru_wave_unit(const Params& p, int l, bf16_t* Z, LAS unsigned char* ldsw, int b, int ch, int n, int final) {
;     ...
;             for (int k = 0; k < 4; ++k) { const int tt = t0 + t - 3 + k;
;                 if (tt >= 0) { const u32x4 raw = *(const u32x4*)(Z + (rowb + tt) * ZP + ZC_LRUX + chn);
;                     const float x[8] = {bflo(raw.x), bfhi(raw.x), bflo(raw.y), bfhi(raw.y), bflo(raw.z), bfhi(raw.z), bflo(raw.w), bfhi(raw.w)};
; #pragma unroll
;                     for (int e = 0; e < 8; ++e) acc[e] += x[e] * cw[k][e]; } }
.LBB0_1952:
	v_lshl_add_u64 v[22:23], s[6:7], 0, v[74:75]
	v_mad_u64_u32 v[56:57], s[76:77], v22, s34, v[42:43]
	v_mad_i32_i24 v57, v23, s34, v57
	s_waitcnt vmcnt(2)
	v_mov_b64_e32 v[56:57], v[200:201]
	v_mov_b64_e32 v[58:59], v[202:203]
	v_lshlrev_b32_e32 v62, 16, v58
	v_and_b32_e32 v63, 0xffff0000, v58
	v_lshlrev_b32_e32 v66, 16, v59
	v_and_b32_e32 v67, 0xffff0000, v59
	v_lshlrev_b32_e32 v22, 16, v56
	v_and_b32_e32 v23, 0xffff0000, v56
	v_lshlrev_b32_e32 v60, 16, v57
	v_and_b32_e32 v61, 0xffff0000, v57
	v_pk_fma_f32 v[58:59], v[24:25], v[62:63], v[0:1]
	v_pk_fma_f32 v[62:63], v[26:27], v[66:67], v[2:3]
	v_pk_fma_f32 v[56:57], v[32:33], v[22:23], v[4:5]
	v_pk_fma_f32 v[22:23], v[34:35], v[60:61], v[6:7]
	v_mov_b32_e32 v60, v62
	v_mov_b32_e32 v61, v63
	s_or_b64 exec, exec, s[26:27]
	v_cmp_lt_i32_e32 vcc, -2, v74
	s_and_saveexec_b64 s[26:27], vcc
	s_cbranch_execz .LBB0_1951
.LBB0_1953:
	v_add_u32_e32 v60, -1, v40
	v_mov_b32_e32 v61, v75
	v_lshl_add_u64 v[60:61], s[6:7], 0, v[60:61]
	v_mad_u64_u32 v[66:67], s[76:77], v60, s34, v[42:43]
	v_mad_i32_i24 v67, v61, s34, v67
	s_waitcnt vmcnt(1)
	v_mov_b64_e32 v[66:67], v[204:205]
	v_mov_b64_e32 v[68:69], v[206:207]
	v_lshlrev_b32_e32 v60, 16, v66
	v_and_b32_e32 v61, 0xffff0000, v66
	v_pk_fma_f32 v[56:57], v[12:13], v[60:61], v[56:57]
	v_lshlrev_b32_e32 v60, 16, v67
	v_and_b32_e32 v61, 0xffff0000, v67
	v_pk_fma_f32 v[22:23], v[14:15], v[60:61], v[22:23]
	v_lshlrev_b32_e32 v60, 16, v68
	v_and_b32_e32 v61, 0xffff0000, v68
	v_pk_fma_f32 v[58:59], v[28:29], v[60:61], v[58:59]
	v_lshlrev_b32_e32 v60, 16, v69
	v_and_b32_e32 v61, 0xffff0000, v69
	v_pk_fma_f32 v[60:61], v[30:31], v[60:61], v[62:63]
	s_or_b64 exec, exec, s[26:27]
	v_cmp_lt_i32_e32 vcc, -3, v74
	s_and_saveexec_b64 s[26:27], vcc
	s_cbranch_execz .LBB0_1948
.LBB0_1954:
	v_mov_b32_e32 v41, v75
	v_lshl_add_u64 v[62:63], s[6:7], 0, v[40:41]
	v_mad_u64_u32 v[66:67], s[76:77], v62, s34, v[42:43]
	v_mad_i32_i24 v67, v63, s34, v67
	s_waitcnt vmcnt(0)
	v_mov_b64_e32 v[66:67], v[208:209]
	v_mov_b64_e32 v[68:69], v[210:211]
	v_lshlrev_b32_e32 v62, 16, v66
	v_and_b32_e32 v63, 0xffff0000, v66
	v_pk_fma_f32 v[56:57], v[36:37], v[62:63], v[56:57]
	v_lshlrev_b32_e32 v62, 16, v67
	v_and_b32_e32 v63, 0xffff0000, v67
	v_pk_fma_f32 v[22:23], v[38:39], v[62:63], v[22:23]
	v_lshlrev_b32_e32 v62, 16, v68
	v_and_b32_e32 v63, 0xffff0000, v68
	v_pk_fma_f32 v[58:59], v[16:17], v[62:63], v[58:59]
	v_lshlrev_b32_e32 v62, 16, v69
	v_and_b32_e32 v63, 0xffff0000, v69
	v_pk_fma_f32 v[60:61], v[18:19], v[62:63], v[60:61]
	s_branch .LBB0_1948
